# attention-B: next-K global loads, P.V base-address math and P-slot address moved ahead of the mid-step barrier into the P-write latency shadow
# baseline (speedup 1.0000x reference)
; #define LAS __attribute__((address_space(3)))
; __device__ __forceinline__ unsigned cvt_pk_bf16(float lo, float hi) { unsigned r; asm volatile("v_cvt_pk_bf16_f32 %0, %1, %2" : "=v"(r) : "v"(lo), "v"(hi)); return r; }
; __device__ __forceinline__ void lds_barrier() { asm volatile("s_waitcnt lgkmcnt(0)" ::: "memory"); __builtin_amdgcn_s_barrier(); asm volatile("" ::: "memory"); }
; __device__ void attn_pair_block(LAS unsigned char* lds, const bf16_t* Qp, const bf16_t* Kp, const bf16_t* Vp, int qb, bf16_t* outp, const float negMB) {
;     ...
;             for (int s2 = 0; s2 < 2; ++s2) { u32x4 w0;
;                 w0.x = cvt_pk_bf16(s0[8 * s2 + 0], s0[8 * s2 + 1]); w0.y = cvt_pk_bf16(s0[8 * s2 + 2], s0[8 * s2 + 3]); w0.z = cvt_pk_bf16(s0[8 * s2 + 4], s0[8 * s2 + 5]); w0.w = cvt_pk_bf16(s0[8 * s2 + 6], s0[8 * s2 + 7]);
;                 pown[s2] = __builtin_bit_cast(bf16x8, w0); *(LAS u32x4*)(xmine + s2 * 1024) = w0; }
;         }
;         lds_barrier();
;         if (act) {
;             bf16x8 poth[2];
; #pragma unroll
;             for (int s2 = 0; s2 < 2; ++s2) poth[s2] = *(const LAS bf16x8*)(xother + s2 * 1024);
;             __builtin_amdgcn_s_setprio(1);
; #pragma unroll
;             for (int st = 0; st < 2; ++st)
; #pragma unroll
;                 for (int s2 = 0; s2 < 2; ++s2)
; #pragma unroll
;                     for (int d = 0; d < 4; ++d) {
;                         const s16x4 lo = __builtin_amdgcn_ds_read_tr16_b64_v4i16((LAS s16x4*)(vb + vread + (32 * st + 16 * s2) * VP2 + d * 64));
;                         const s16x4 hi = __builtin_amdgcn_ds_read_tr16_b64_v4i16((LAS s16x4*)(vb + vread + (32 * st + 16 * s2 + 8) * VP2 + d * 64));
;                         const bf16x8 vf = __builtin_shufflevector(lo, hi, 0, 1, 2, 3, 4, 5, 6, 7);
;                         const bf16x8 pfr = (st == stw) ? pown[s2] : poth[s2];
;                         o[d] = __builtin_amdgcn_mfma_f32_32x32x16_bf16(vf, pfr, o[d], 0, 0, 0);
.LBB0_809:
	s_nop 10
	v_exp_f32_e32 v80, v80
	v_exp_f32_e32 v81, v81
	v_exp_f32_e32 v82, v82
	v_exp_f32_e32 v83, v83
	v_exp_f32_e32 v193, v84
	v_add_f32_e32 v84, 0, v80
	v_exp_f32_e32 v194, v85
	v_add_f32_e32 v84, v81, v84
	v_exp_f32_e32 v195, v86
	v_add_f32_e32 v84, v82, v84
	v_exp_f32_e32 v87, v87
	v_add_f32_e32 v84, v83, v84
	v_exp_f32_e32 v88, v88
	v_add_f32_e32 v84, v193, v84
	v_exp_f32_e32 v89, v89
	v_add_f32_e32 v84, v194, v84
	v_exp_f32_e32 v90, v90
	v_add_f32_e32 v84, v195, v84
	v_exp_f32_e32 v91, v91
	v_add_f32_e32 v84, v87, v84
	v_exp_f32_e32 v92, v92
	v_add_f32_e32 v84, v88, v84
	v_exp_f32_e32 v93, v93
	v_add_f32_e32 v84, v89, v84
	v_exp_f32_e32 v94, v94
	v_add_f32_e32 v84, v90, v84
	v_exp_f32_e32 v95, v95
	v_add_f32_e32 v84, v91, v84
	v_add_f32_e32 v84, v92, v84
	v_add_f32_e32 v84, v93, v84
	v_add_f32_e32 v84, v94, v84
	v_add_f32_e32 v196, v95, v84
	v_cvt_pk_bf16_f32 v84, v80, v81
	v_cvt_pk_bf16_f32 v85, v82, v83
	v_cvt_pk_bf16_f32 v86, v193, v194
	s_bitcmp1_b32 s20, 0
	s_cselect_b32 s25, 0x7840, 0
	s_add_i32 s25, s25, s13
	v_add_u32_e32 v193, s25, v163
	v_add_f32_e32 v167, v167, v196
	v_cvt_pk_bf16_f32 v87, v195, v87
	ds_write_b128 v193, v[84:87]
	v_cvt_pk_bf16_f32 v80, v88, v89
	v_cvt_pk_bf16_f32 v81, v90, v91
	v_cvt_pk_bf16_f32 v82, v92, v93
	v_cvt_pk_bf16_f32 v83, v94, v95
	ds_write_b128 v193, v[80:83] offset:1024
	s_mul_i32 s24, s12, 0x4800
	s_add_i32 s25, s14, s23
	v_add_u32_e32 v193, s25, v169
	v_add3_u32 v193, v193, v171, v173
	s_sub_i32 s25, 0x4800, s24
	v_add_u32_e32 v194, s25, v193
	v_add_u32_e32 v193, s24, v193
	s_bitcmp1_b32 s20, 0
	s_cselect_b32 s25, 0x7840, 0
	s_add_i32 s25, s25, s15
	v_add_u32_e32 v92, s25, v163
.LBB0_810:
	global_load_dwordx4 v[128:131], v250, s[100:101]
	global_load_dwordx4 v[136:139], v251, s[100:101]
	s_add_u32 s100, s100, 0x20000
	s_addc_u32 s101, s101, 0
	s_waitcnt lgkmcnt(0)
	s_barrier
	s_andn2_b64 vcc, exec, s[8:9]
	s_cbranch_vccnz .LBB0_805
	ds_read_b128 v[88:91], v92
	ds_read_b128 v[92:95], v92 offset:1024
	s_setprio 1
	ds_read_b64_tr_b16 v[198:199], v193 offset:17408
	ds_read_b64_tr_b16 v[200:201], v193 offset:22016
	ds_read_b64_tr_b16 v[202:203], v193 offset:17472
	ds_read_b64_tr_b16 v[204:205], v193 offset:22080
	ds_read_b64_tr_b16 v[206:207], v193 offset:17536
	ds_read_b64_tr_b16 v[208:209], v193 offset:22144
	ds_read_b64_tr_b16 v[210:211], v193 offset:17600
	ds_read_b64_tr_b16 v[212:213], v193 offset:22208
	s_add_i32 s24, s20, 1
	s_bitcmp1_b32 s24, 0
	s_cselect_b32 s23, 0xd400, 0
	v_add_u32_e32 v242, s23, v162
	v_add_u32_e32 v243, v242, v188
	v_add_u32_e32 v244, v242, v189
	v_add_u32_e32 v245, v242, v190
	v_add_u32_e32 v242, v242, v191
	s_waitcnt lgkmcnt(6)
	v_mfma_f32_32x32x16_bf16 v[64:79], v[198:201], v[84:87], v[64:79]
	ds_read_b64_tr_b16 v[198:199], v193 offset:26624
	ds_read_b64_tr_b16 v[200:201], v193 offset:31232
	s_waitcnt lgkmcnt(6)
	v_mfma_f32_32x32x16_bf16 v[48:63], v[202:205], v[84:87], v[48:63]
	ds_read_b64_tr_b16 v[202:203], v193 offset:26688
	ds_read_b64_tr_b16 v[204:205], v193 offset:31296
	s_waitcnt lgkmcnt(6)
	v_mfma_f32_32x32x16_bf16 v[32:47], v[206:209], v[84:87], v[32:47]
	ds_read_b64_tr_b16 v[206:207], v193 offset:26752
	ds_read_b64_tr_b16 v[208:209], v193 offset:31360
	s_waitcnt vmcnt(5)
	ds_write_b128 v243, v[132:135] offset:17408
	s_waitcnt lgkmcnt(7)
	v_mfma_f32_32x32x16_bf16 v[16:31], v[210:213], v[84:87], v[16:31]
	ds_read_b64_tr_b16 v[210:211], v193 offset:26816
	ds_read_b64_tr_b16 v[212:213], v193 offset:31424
	s_waitcnt lgkmcnt(7)
	v_mfma_f32_32x32x16_bf16 v[64:79], v[198:201], v[80:83], v[64:79]
	ds_read_b64_tr_b16 v[198:199], v194 offset:17408
	ds_read_b64_tr_b16 v[200:201], v194 offset:22016
	s_waitcnt lgkmcnt(7)
	v_mfma_f32_32x32x16_bf16 v[48:63], v[202:205], v[80:83], v[48:63]
	ds_read_b64_tr_b16 v[202:203], v194 offset:17472
	ds_read_b64_tr_b16 v[204:205], v194 offset:22080
	s_waitcnt vmcnt(4)
	ds_write_b128 v244, v[144:147] offset:17408
	s_waitcnt lgkmcnt(8)
	v_mfma_f32_32x32x16_bf16 v[32:47], v[206:209], v[80:83], v[32:47]
	ds_read_b64_tr_b16 v[206:207], v194 offset:17536
	ds_read_b64_tr_b16 v[208:209], v194 offset:22144
	s_waitcnt lgkmcnt(7)
	v_mfma_f32_32x32x16_bf16 v[16:31], v[210:213], v[80:83], v[16:31]
	ds_read_b64_tr_b16 v[210:211], v194 offset:17600
	ds_read_b64_tr_b16 v[212:213], v194 offset:22208
	s_waitcnt lgkmcnt(7)
	v_mfma_f32_32x32x16_bf16 v[64:79], v[198:201], v[88:91], v[64:79]
	ds_read_b64_tr_b16 v[198:199], v194 offset:26624
	ds_read_b64_tr_b16 v[200:201], v194 offset:31232
	s_waitcnt vmcnt(3)
	ds_write_b128 v245, v[140:143] offset:17408
	s_waitcnt lgkmcnt(8)
	v_mfma_f32_32x32x16_bf16 v[48:63], v[202:205], v[88:91], v[48:63]
	ds_read_b64_tr_b16 v[202:203], v194 offset:26688
	ds_read_b64_tr_b16 v[204:205], v194 offset:31296
	s_waitcnt lgkmcnt(7)
	v_mfma_f32_32x32x16_bf16 v[32:47], v[206:209], v[88:91], v[32:47]
	ds_read_b64_tr_b16 v[206:207], v194 offset:26752
	ds_read_b64_tr_b16 v[208:209], v194 offset:31360
	s_waitcnt lgkmcnt(7)
	v_mfma_f32_32x32x16_bf16 v[16:31], v[210:213], v[88:91], v[16:31]
	ds_read_b64_tr_b16 v[210:211], v194 offset:26816
	ds_read_b64_tr_b16 v[212:213], v194 offset:31424
	s_waitcnt vmcnt(2)
	ds_write_b128 v242, v[148:151] offset:17408
	s_waitcnt lgkmcnt(8)
	v_mfma_f32_32x32x16_bf16 v[64:79], v[198:201], v[92:95], v[64:79]
	s_waitcnt lgkmcnt(5)
	v_mfma_f32_32x32x16_bf16 v[48:63], v[202:205], v[92:95], v[48:63]
	s_waitcnt lgkmcnt(3)
	v_mfma_f32_32x32x16_bf16 v[32:47], v[206:209], v[92:95], v[32:47]
	s_waitcnt lgkmcnt(1)
	v_mfma_f32_32x32x16_bf16 v[16:31], v[210:213], v[92:95], v[16:31]
	s_setprio 0
	s_add_i32 s20, s20, 1
	s_branch .Lpb_tail
